# as before, staging poll interval doubled
# baseline (speedup 1.0000x reference)
.Lsc_G_pollm0:
	s_sleep 24
	ds_read_b128 v[148:151], v144
	s_waitcnt lgkmcnt(0)
	v_min_u32_e32 v148, v148, v149
	v_min3_u32 v148, v148, v150, v151
	s_sub_u32 s69, s69, 1
	s_nop 1
	v_readfirstlane_b32 s68, v148
	s_cmp_eq_u32 s69, 0
	s_cbranch_scc1 .Lsc_G_gom0
	s_cmp_lt_u32 s68, s65
	s_cbranch_scc1 .Lsc_G_pollm0
